# own lean helper waves + 2x4 recurrence, recurrence loop placed at 48 mod 64 (one s_nop pad before the loop)
# speedup vs baseline: 1.0019x; 1.0019x over previous
.LBB0_606:
	s_and_b64 vcc, exec, s[0:1]
	s_cbranch_vccz .LBB0_508
	s_waitcnt vmcnt(0)
	v_lshrrev_b32_e32 v90, 4, v241
	v_bfe_u32 v91, v241, 3, 1
	v_and_b32_e32 v86, 15, v241
	v_lshlrev_b32_e32 v90, 1, v90
	v_lshlrev_b32_e32 v86, 4, v86
	v_add_u32_e32 v92, v90, v91
	v_xor_b32_e32 v91, 1, v91
	v_add_u32_e32 v93, v90, v91
	s_lshl_b32 s0, s10, 5
	v_lshlrev_b32_e32 v89, 2, v92
	v_add_u32_e32 v92, s0, v92
	v_add_u32_e32 v93, s0, v93
	v_add_u32_e32 v89, 0x18000, v89
	v_lshlrev_b32_e32 v87, 2, v92
	v_lshlrev_b32_e32 v88, 2, v93
	v_mov_b32_e32 v0, 0
	v_mov_b32_e32 v1, 0
	v_mov_b32_e32 v2, 0
	v_mov_b32_e32 v3, 0
	v_mov_b32_e32 v4, 0
	v_mov_b32_e32 v5, 0
	v_mov_b32_e32 v6, 0
	v_mov_b32_e32 v7, 0
	s_waitcnt lgkmcnt(0)
	s_barrier
	s_mov_b32 s4, 0
	s_nop 0
